# m2 scan: double-buffered 16-chunk batches (next batch loads issued into shadow registers at the top of the current batch)
# baseline (speedup 1.0000x reference)
.LBB0_360:
	s_mov_b32 s4, 0xfe03f81
	v_mul_hi_i32 v0, v44, s4
	v_lshrrev_b32_e32 v1, 31, v0
	v_ashrrev_i32_e32 v0, 8, v0
	v_add_u32_e32 v0, v0, v1
	v_mul_i32_i24_e32 v1, 0x1020, v0
	v_sub_u32_e32 v2, v44, v1
	v_ashrrev_i32_e32 v1, 31, v0
	v_mul_hi_i32_i24_e32 v5, 0x204000, v0
	v_mul_i32_i24_e32 v4, 0x204000, v0
	v_ashrrev_i32_e32 v3, 31, v2
	v_mov_b32_e32 v34, 0
	v_lshlrev_b64 v[0:1], 11, v[0:1]
	v_cmp_eq_u32_e64 s[4:5], 0, v2
	v_lshl_add_u64 v[2:3], v[2:3], 2, v[4:5]
	v_mov_b32_e32 v59, 0xf149f2ca
	s_mov_b32 s10, -16
	v_mov_b32_e32 v35, v34
	s_waitcnt lgkmcnt(0)
	s_add_u32 s90, s2, 0x18200000
	s_addc_u32 s91, s3, 0
	s_add_u32 s92, s2, 0x18100000
	s_addc_u32 s93, s3, 0
	v_mov_b32_e32 v148, v2
	v_mov_b32_e32 v149, v0
	global_load_dword v100, v148, s[90:91]
	global_load_dwordx2 v[116:117], v149, s[92:93]
	s_add_u32 s90, s90, 0x4080
	s_addc_u32 s91, s91, 0
	global_load_dword v101, v148, s[90:91]
	global_load_dwordx2 v[118:119], v149, s[92:93] offset:16
	s_add_u32 s90, s90, 0x4080
	s_addc_u32 s91, s91, 0
	global_load_dword v102, v148, s[90:91]
	global_load_dwordx2 v[120:121], v149, s[92:93] offset:32
	s_add_u32 s90, s90, 0x4080
	s_addc_u32 s91, s91, 0
	global_load_dword v103, v148, s[90:91]
	global_load_dwordx2 v[122:123], v149, s[92:93] offset:48
	s_add_u32 s90, s90, 0x4080
	s_addc_u32 s91, s91, 0
	global_load_dword v104, v148, s[90:91]
	global_load_dwordx2 v[124:125], v149, s[92:93] offset:64
	s_add_u32 s90, s90, 0x4080
	s_addc_u32 s91, s91, 0
	global_load_dword v105, v148, s[90:91]
	global_load_dwordx2 v[126:127], v149, s[92:93] offset:80
	s_add_u32 s90, s90, 0x4080
	s_addc_u32 s91, s91, 0
	global_load_dword v106, v148, s[90:91]
	global_load_dwordx2 v[128:129], v149, s[92:93] offset:96
	s_add_u32 s90, s90, 0x4080
	s_addc_u32 s91, s91, 0
	global_load_dword v107, v148, s[90:91]
	global_load_dwordx2 v[130:131], v149, s[92:93] offset:112
	s_add_u32 s90, s90, 0x4080
	s_addc_u32 s91, s91, 0
	global_load_dword v108, v148, s[90:91]
	global_load_dwordx2 v[132:133], v149, s[92:93] offset:128
	s_add_u32 s90, s90, 0x4080
	s_addc_u32 s91, s91, 0
	global_load_dword v109, v148, s[90:91]
	global_load_dwordx2 v[134:135], v149, s[92:93] offset:144
	s_add_u32 s90, s90, 0x4080
	s_addc_u32 s91, s91, 0
	global_load_dword v110, v148, s[90:91]
	global_load_dwordx2 v[136:137], v149, s[92:93] offset:160
	s_add_u32 s90, s90, 0x4080
	s_addc_u32 s91, s91, 0
	global_load_dword v111, v148, s[90:91]
	global_load_dwordx2 v[138:139], v149, s[92:93] offset:176
	s_add_u32 s90, s90, 0x4080
	s_addc_u32 s91, s91, 0
	global_load_dword v112, v148, s[90:91]
	global_load_dwordx2 v[140:141], v149, s[92:93] offset:192
	s_add_u32 s90, s90, 0x4080
	s_addc_u32 s91, s91, 0
	global_load_dword v113, v148, s[90:91]
	global_load_dwordx2 v[142:143], v149, s[92:93] offset:208
	s_add_u32 s90, s90, 0x4080
	s_addc_u32 s91, s91, 0
	global_load_dword v114, v148, s[90:91]
	global_load_dwordx2 v[144:145], v149, s[92:93] offset:224
	s_add_u32 s90, s90, 0x4080
	s_addc_u32 s91, s91, 0
	global_load_dword v115, v148, s[90:91]
	global_load_dwordx2 v[146:147], v149, s[92:93] offset:240
	s_add_u32 s90, s90, 0x4080
	s_addc_u32 s91, s91, 0
	s_add_u32 s92, s92, 0x100
	s_addc_u32 s93, s93, 0
	s_waitcnt vmcnt(0)
	s_branch .LBB0_362
.LBB0_361:
	s_or_b64 exec, exec, s[8:9]
	v_add_f32_e32 v4, v9, v13
	v_max_f32_e32 v5, v12, v12
	v_max_f32_e32 v59, v4, v5
	v_sub_f32_e32 v4, v4, v59
	v_mul_f32_e32 v5, 0x3fb8aa3b, v4
	v_sub_f32_e32 v4, v12, v59
	v_mul_f32_e32 v4, 0x3fb8aa3b, v4
	v_exp_f32_e32 v4, v4
	v_exp_f32_e32 v8, v5
	v_lshlrev_b32_e32 v10, 16, v46
	v_and_b32_e32 v11, 0xffff0000, v46
	s_mov_b64 s[8:9], 0x100
	v_pk_mul_f32 v[4:5], v[4:5], v[10:11] op_sel_hi:[0,1]
	s_add_i32 s10, s10, 16
	v_lshl_add_u64 v[0:1], v[0:1], 0, s[8:9]
	s_mov_b64 s[8:9], 0x40800
	v_pk_fma_f32 v[34:35], v[6:7], v[8:9], v[4:5] op_sel_hi:[1,0,1]
	s_cmpk_gt_u32 s10, 0x6f
	v_lshl_add_u64 v[2:3], v[2:3], 0, s[8:9]
	s_cbranch_scc1 .LBB0_359
.LBB0_362:
	s_waitcnt lgkmcnt(0)
	v_lshl_add_u64 v[6:7], s[2:3], 0, v[2:3]
	v_add_co_u32_e32 v42, vcc, 0x18200000, v6
	v_lshl_add_u64 v[4:5], s[2:3], 0, v[0:1]
	s_nop 0
	v_addc_co_u32_e32 v43, vcc, 0, v7, vcc
	s_waitcnt vmcnt(16)
	v_mov_b32_e32 v61, v100
	v_mov_b32_e32 v60, v101
	v_mov_b32_e32 v58, v102
	v_mov_b32_e32 v57, v103
	v_mov_b32_e32 v56, v104
	v_mov_b32_e32 v55, v105
	v_mov_b32_e32 v54, v106
	v_mov_b32_e32 v53, v107
	v_mov_b32_e32 v52, v108
	v_mov_b32_e32 v51, v109
	v_mov_b32_e32 v50, v110
	v_mov_b32_e32 v49, v111
	v_mov_b32_e32 v48, v112
	v_mov_b32_e32 v47, v113
	v_mov_b32_e32 v45, v114
	v_mov_b32_e32 v46, v115
	v_mov_b64_e32 v[40:41], v[116:117]
	v_mov_b64_e32 v[38:39], v[118:119]
	v_mov_b64_e32 v[36:37], v[120:121]
	v_mov_b64_e32 v[32:33], v[122:123]
	v_mov_b64_e32 v[30:31], v[124:125]
	v_mov_b64_e32 v[28:29], v[126:127]
	v_mov_b64_e32 v[26:27], v[128:129]
	v_mov_b64_e32 v[24:25], v[130:131]
	v_mov_b64_e32 v[22:23], v[132:133]
	v_mov_b64_e32 v[20:21], v[134:135]
	v_mov_b64_e32 v[18:19], v[136:137]
	v_mov_b64_e32 v[16:17], v[138:139]
	v_mov_b64_e32 v[14:15], v[140:141]
	v_mov_b64_e32 v[10:11], v[142:143]
	v_mov_b64_e32 v[8:9], v[144:145]
	v_mov_b64_e32 v[12:13], v[146:147]
	s_cmp_eq_u32 s10, 0x60
	s_cbranch_scc1 .Lm2_nopf
	global_load_dword v100, v148, s[90:91]
	global_load_dwordx2 v[116:117], v149, s[92:93]
	s_add_u32 s90, s90, 0x4080
	s_addc_u32 s91, s91, 0
	global_load_dword v101, v148, s[90:91]
	global_load_dwordx2 v[118:119], v149, s[92:93] offset:16
	s_add_u32 s90, s90, 0x4080
	s_addc_u32 s91, s91, 0
	global_load_dword v102, v148, s[90:91]
	global_load_dwordx2 v[120:121], v149, s[92:93] offset:32
	s_add_u32 s90, s90, 0x4080
	s_addc_u32 s91, s91, 0
	global_load_dword v103, v148, s[90:91]
	global_load_dwordx2 v[122:123], v149, s[92:93] offset:48
	s_add_u32 s90, s90, 0x4080
	s_addc_u32 s91, s91, 0
	global_load_dword v104, v148, s[90:91]
	global_load_dwordx2 v[124:125], v149, s[92:93] offset:64
	s_add_u32 s90, s90, 0x4080
	s_addc_u32 s91, s91, 0
	global_load_dword v105, v148, s[90:91]
	global_load_dwordx2 v[126:127], v149, s[92:93] offset:80
	s_add_u32 s90, s90, 0x4080
	s_addc_u32 s91, s91, 0
	global_load_dword v106, v148, s[90:91]
	global_load_dwordx2 v[128:129], v149, s[92:93] offset:96
	s_add_u32 s90, s90, 0x4080
	s_addc_u32 s91, s91, 0
	global_load_dword v107, v148, s[90:91]
	global_load_dwordx2 v[130:131], v149, s[92:93] offset:112
	s_add_u32 s90, s90, 0x4080
	s_addc_u32 s91, s91, 0
	global_load_dword v108, v148, s[90:91]
	global_load_dwordx2 v[132:133], v149, s[92:93] offset:128
	s_add_u32 s90, s90, 0x4080
	s_addc_u32 s91, s91, 0
	global_load_dword v109, v148, s[90:91]
	global_load_dwordx2 v[134:135], v149, s[92:93] offset:144
	s_add_u32 s90, s90, 0x4080
	s_addc_u32 s91, s91, 0
	global_load_dword v110, v148, s[90:91]
	global_load_dwordx2 v[136:137], v149, s[92:93] offset:160
	s_add_u32 s90, s90, 0x4080
	s_addc_u32 s91, s91, 0
	global_load_dword v111, v148, s[90:91]
	global_load_dwordx2 v[138:139], v149, s[92:93] offset:176
	s_add_u32 s90, s90, 0x4080
	s_addc_u32 s91, s91, 0
	global_load_dword v112, v148, s[90:91]
	global_load_dwordx2 v[140:141], v149, s[92:93] offset:192
	s_add_u32 s90, s90, 0x4080
	s_addc_u32 s91, s91, 0
	global_load_dword v113, v148, s[90:91]
	global_load_dwordx2 v[142:143], v149, s[92:93] offset:208
	s_add_u32 s90, s90, 0x4080
	s_addc_u32 s91, s91, 0
	global_load_dword v114, v148, s[90:91]
	global_load_dwordx2 v[144:145], v149, s[92:93] offset:224
	s_add_u32 s90, s90, 0x4080
	s_addc_u32 s91, s91, 0
	global_load_dword v115, v148, s[90:91]
	global_load_dwordx2 v[146:147], v149, s[92:93] offset:240
	s_add_u32 s90, s90, 0x4080
	s_addc_u32 s91, s91, 0
	s_add_u32 s92, s92, 0x100
	s_addc_u32 s93, s93, 0
.Lm2_nopf:
	v_cvt_pk_bf16_f32 v62, v34, v35
	global_store_dword v[42:43], v62, off
	s_and_saveexec_b64 s[8:9], s[4:5]
	s_cbranch_execz .LBB0_364
	v_add_co_u32_e32 v42, vcc, 0x18100000, v4
	s_nop 1
	v_addc_co_u32_e32 v43, vcc, 0, v5, vcc
	global_store_dword v[42:43], v59, off offset:8
.LBB0_364:
	s_or_b64 exec, exec, s[8:9]
	v_add_f32_e32 v59, v59, v41
	v_max_f32_e32 v41, v40, v40
	v_max_f32_e32 v41, v59, v41
	v_sub_f32_e32 v40, v40, v41
	v_sub_f32_e32 v59, v59, v41
	v_mul_f32_e32 v40, 0x3fb8aa3b, v40
	v_mul_f32_e32 v59, 0x3fb8aa3b, v59
	v_exp_f32_e32 v40, v40
	v_exp_f32_e32 v62, v59
	v_lshlrev_b32_e32 v64, 16, v61
	v_and_b32_e32 v65, 0xffff0000, v61
	v_pk_mul_f32 v[64:65], v[40:41], v[64:65] op_sel_hi:[0,1]
	s_mov_b64 s[8:9], 0x18204080
	v_pk_fma_f32 v[34:35], v[34:35], v[62:63], v[64:65] op_sel_hi:[1,0,1]
	v_lshl_add_u64 v[42:43], v[6:7], 0, s[8:9]
	v_cvt_pk_bf16_f32 v40, v34, v35
	global_store_dword v[42:43], v40, off
	s_and_saveexec_b64 s[8:9], s[4:5]
	s_cbranch_execz .LBB0_366
	v_add_co_u32_e32 v42, vcc, 0x18100000, v4
	s_nop 1
	v_addc_co_u32_e32 v43, vcc, 0, v5, vcc
	global_store_dword v[42:43], v41, off offset:24
.LBB0_366:
	s_or_b64 exec, exec, s[8:9]
	v_add_f32_e32 v40, v41, v39
	v_max_f32_e32 v39, v38, v38
	v_max_f32_e32 v39, v40, v39
	v_sub_f32_e32 v38, v38, v39
	v_sub_f32_e32 v40, v40, v39
	v_mul_f32_e32 v38, 0x3fb8aa3b, v38
	v_mul_f32_e32 v40, 0x3fb8aa3b, v40
	v_exp_f32_e32 v38, v38
	v_exp_f32_e32 v40, v40
	v_lshlrev_b32_e32 v62, 16, v60
	v_and_b32_e32 v63, 0xffff0000, v60
	v_pk_mul_f32 v[60:61], v[38:39], v[62:63] op_sel_hi:[0,1]
	s_mov_b64 s[8:9], 0x18208100
	v_pk_fma_f32 v[34:35], v[34:35], v[40:41], v[60:61] op_sel_hi:[1,0,1]
	v_lshl_add_u64 v[42:43], v[6:7], 0, s[8:9]
	v_cvt_pk_bf16_f32 v38, v34, v35
	global_store_dword v[42:43], v38, off
	s_and_saveexec_b64 s[8:9], s[4:5]
	s_cbranch_execz .LBB0_368
	v_add_co_u32_e32 v40, vcc, 0x18100000, v4
	s_nop 1
	v_addc_co_u32_e32 v41, vcc, 0, v5, vcc
	global_store_dword v[40:41], v39, off offset:40
.LBB0_368:
	s_or_b64 exec, exec, s[8:9]
	v_add_f32_e32 v38, v39, v37
	v_max_f32_e32 v37, v36, v36
	v_max_f32_e32 v37, v38, v37
	v_sub_f32_e32 v36, v36, v37
	v_sub_f32_e32 v38, v38, v37
	v_mul_f32_e32 v36, 0x3fb8aa3b, v36
	v_mul_f32_e32 v38, 0x3fb8aa3b, v38
	v_exp_f32_e32 v36, v36
	v_exp_f32_e32 v38, v38
	v_lshlrev_b32_e32 v42, 16, v58
	v_and_b32_e32 v43, 0xffff0000, v58
	v_pk_mul_f32 v[42:43], v[36:37], v[42:43] op_sel_hi:[0,1]
	s_mov_b64 s[8:9], 0x1820c180
	v_pk_fma_f32 v[34:35], v[34:35], v[38:39], v[42:43] op_sel_hi:[1,0,1]
	v_lshl_add_u64 v[40:41], v[6:7], 0, s[8:9]
	v_cvt_pk_bf16_f32 v36, v34, v35
	global_store_dword v[40:41], v36, off
	s_and_saveexec_b64 s[8:9], s[4:5]
	s_cbranch_execz .LBB0_370
	v_add_co_u32_e32 v38, vcc, 0x18100000, v4
	s_nop 1
	v_addc_co_u32_e32 v39, vcc, 0, v5, vcc
	global_store_dword v[38:39], v37, off offset:56
.LBB0_370:
	s_or_b64 exec, exec, s[8:9]
	v_add_f32_e32 v33, v37, v33
	v_max_f32_e32 v36, v32, v32
	v_max_f32_e32 v36, v33, v36
	v_sub_f32_e32 v32, v32, v36
	v_sub_f32_e32 v33, v33, v36
	v_mul_f32_e32 v32, 0x3fb8aa3b, v32
	v_mul_f32_e32 v33, 0x3fb8aa3b, v33
	v_exp_f32_e32 v32, v32
	v_exp_f32_e32 v40, v33
	v_lshlrev_b32_e32 v42, 16, v57
	v_and_b32_e32 v43, 0xffff0000, v57
	v_pk_mul_f32 v[32:33], v[32:33], v[42:43] op_sel_hi:[0,1]
	s_mov_b64 s[8:9], 0x18210200
	v_pk_fma_f32 v[32:33], v[34:35], v[40:41], v[32:33] op_sel_hi:[1,0,1]
	v_lshl_add_u64 v[38:39], v[6:7], 0, s[8:9]
	v_cvt_pk_bf16_f32 v34, v32, v33
	global_store_dword v[38:39], v34, off
	s_and_saveexec_b64 s[8:9], s[4:5]
	s_cbranch_execz .LBB0_372
	v_add_co_u32_e32 v34, vcc, 0x18100000, v4
	s_nop 1
	v_addc_co_u32_e32 v35, vcc, 0, v5, vcc
	global_store_dword v[34:35], v36, off offset:72
.LBB0_372:
	s_or_b64 exec, exec, s[8:9]
	v_add_f32_e32 v31, v36, v31
	v_max_f32_e32 v34, v30, v30
	v_max_f32_e32 v34, v31, v34
	v_sub_f32_e32 v30, v30, v34
	v_sub_f32_e32 v31, v31, v34
	v_mul_f32_e32 v30, 0x3fb8aa3b, v30
	v_mul_f32_e32 v31, 0x3fb8aa3b, v31
	v_exp_f32_e32 v30, v30
	v_exp_f32_e32 v36, v31
	v_lshlrev_b32_e32 v40, 16, v56
	v_and_b32_e32 v41, 0xffff0000, v56
	v_pk_mul_f32 v[30:31], v[30:31], v[40:41] op_sel_hi:[0,1]
	s_mov_b64 s[8:9], 0x18214280
	v_pk_fma_f32 v[30:31], v[32:33], v[36:37], v[30:31] op_sel_hi:[1,0,1]
	v_lshl_add_u64 v[38:39], v[6:7], 0, s[8:9]
	v_cvt_pk_bf16_f32 v32, v30, v31
	global_store_dword v[38:39], v32, off
	s_and_saveexec_b64 s[8:9], s[4:5]
	s_cbranch_execz .LBB0_374
	v_add_co_u32_e32 v32, vcc, 0x18100000, v4
	s_nop 1
	v_addc_co_u32_e32 v33, vcc, 0, v5, vcc
	global_store_dword v[32:33], v34, off offset:88
.LBB0_374:
	s_or_b64 exec, exec, s[8:9]
	v_add_f32_e32 v29, v34, v29
	v_max_f32_e32 v32, v28, v28
	v_max_f32_e32 v32, v29, v32
	v_sub_f32_e32 v28, v28, v32
	v_sub_f32_e32 v29, v29, v32
	v_mul_f32_e32 v28, 0x3fb8aa3b, v28
	v_mul_f32_e32 v29, 0x3fb8aa3b, v29
	v_exp_f32_e32 v28, v28
	v_exp_f32_e32 v34, v29
	v_lshlrev_b32_e32 v38, 16, v55
	v_and_b32_e32 v39, 0xffff0000, v55
	v_pk_mul_f32 v[28:29], v[28:29], v[38:39] op_sel_hi:[0,1]
	s_mov_b64 s[8:9], 0x18218300
	v_pk_fma_f32 v[28:29], v[30:31], v[34:35], v[28:29] op_sel_hi:[1,0,1]
	v_lshl_add_u64 v[36:37], v[6:7], 0, s[8:9]
	v_cvt_pk_bf16_f32 v30, v28, v29
	global_store_dword v[36:37], v30, off
	s_and_saveexec_b64 s[8:9], s[4:5]
	s_cbranch_execz .LBB0_376
	v_add_co_u32_e32 v30, vcc, 0x18100000, v4
	s_nop 1
	v_addc_co_u32_e32 v31, vcc, 0, v5, vcc
	global_store_dword v[30:31], v32, off offset:104
.LBB0_376:
	s_or_b64 exec, exec, s[8:9]
	v_add_f32_e32 v27, v32, v27
	v_max_f32_e32 v30, v26, v26
	v_max_f32_e32 v30, v27, v30
	v_sub_f32_e32 v26, v26, v30
	v_sub_f32_e32 v27, v27, v30
	v_mul_f32_e32 v26, 0x3fb8aa3b, v26
	v_mul_f32_e32 v27, 0x3fb8aa3b, v27
	v_exp_f32_e32 v26, v26
	v_exp_f32_e32 v32, v27
	v_lshlrev_b32_e32 v36, 16, v54
	v_and_b32_e32 v37, 0xffff0000, v54
	v_pk_mul_f32 v[26:27], v[26:27], v[36:37] op_sel_hi:[0,1]
	s_mov_b64 s[8:9], 0x1821c380
	v_pk_fma_f32 v[26:27], v[28:29], v[32:33], v[26:27] op_sel_hi:[1,0,1]
	v_lshl_add_u64 v[34:35], v[6:7], 0, s[8:9]
	v_cvt_pk_bf16_f32 v28, v26, v27
	global_store_dword v[34:35], v28, off
	s_and_saveexec_b64 s[8:9], s[4:5]
	s_cbranch_execz .LBB0_378
	v_add_co_u32_e32 v28, vcc, 0x18100000, v4
	s_nop 1
	v_addc_co_u32_e32 v29, vcc, 0, v5, vcc
	global_store_dword v[28:29], v30, off offset:120
.LBB0_378:
	s_or_b64 exec, exec, s[8:9]
	v_add_f32_e32 v25, v30, v25
	v_max_f32_e32 v28, v24, v24
	v_max_f32_e32 v28, v25, v28
	v_sub_f32_e32 v24, v24, v28
	v_sub_f32_e32 v25, v25, v28
	v_mul_f32_e32 v24, 0x3fb8aa3b, v24
	v_mul_f32_e32 v25, 0x3fb8aa3b, v25
	v_exp_f32_e32 v24, v24
	v_exp_f32_e32 v30, v25
	v_lshlrev_b32_e32 v34, 16, v53
	v_and_b32_e32 v35, 0xffff0000, v53
	v_pk_mul_f32 v[24:25], v[24:25], v[34:35] op_sel_hi:[0,1]
	s_mov_b64 s[8:9], 0x18220400
	v_pk_fma_f32 v[24:25], v[26:27], v[30:31], v[24:25] op_sel_hi:[1,0,1]
	v_lshl_add_u64 v[32:33], v[6:7], 0, s[8:9]
	v_cvt_pk_bf16_f32 v26, v24, v25
	global_store_dword v[32:33], v26, off
	s_and_saveexec_b64 s[8:9], s[4:5]
	s_cbranch_execz .LBB0_380
	v_add_co_u32_e32 v26, vcc, 0x18100000, v4
	s_nop 1
	v_addc_co_u32_e32 v27, vcc, 0, v5, vcc
	global_store_dword v[26:27], v28, off offset:136
.LBB0_380:
	s_or_b64 exec, exec, s[8:9]
	v_add_f32_e32 v23, v28, v23
	v_max_f32_e32 v26, v22, v22
	v_max_f32_e32 v26, v23, v26
	v_sub_f32_e32 v22, v22, v26
	v_sub_f32_e32 v23, v23, v26
	v_mul_f32_e32 v22, 0x3fb8aa3b, v22
	v_mul_f32_e32 v23, 0x3fb8aa3b, v23
	v_exp_f32_e32 v22, v22
	v_exp_f32_e32 v28, v23
	v_lshlrev_b32_e32 v32, 16, v52
	v_and_b32_e32 v33, 0xffff0000, v52
	v_pk_mul_f32 v[22:23], v[22:23], v[32:33] op_sel_hi:[0,1]
	s_mov_b64 s[8:9], 0x18224480
	v_pk_fma_f32 v[22:23], v[24:25], v[28:29], v[22:23] op_sel_hi:[1,0,1]
	v_lshl_add_u64 v[30:31], v[6:7], 0, s[8:9]
	v_cvt_pk_bf16_f32 v24, v22, v23
	global_store_dword v[30:31], v24, off
	s_and_saveexec_b64 s[8:9], s[4:5]
	s_cbranch_execz .LBB0_382
	v_add_co_u32_e32 v24, vcc, 0x18100000, v4
	s_nop 1
	v_addc_co_u32_e32 v25, vcc, 0, v5, vcc
	global_store_dword v[24:25], v26, off offset:152
.LBB0_382:
	s_or_b64 exec, exec, s[8:9]
	v_add_f32_e32 v21, v26, v21
	v_max_f32_e32 v24, v20, v20
	v_max_f32_e32 v24, v21, v24
	v_sub_f32_e32 v20, v20, v24
	v_sub_f32_e32 v21, v21, v24
	v_mul_f32_e32 v20, 0x3fb8aa3b, v20
	v_mul_f32_e32 v21, 0x3fb8aa3b, v21
	v_exp_f32_e32 v20, v20
	v_exp_f32_e32 v26, v21
	v_lshlrev_b32_e32 v30, 16, v51
	v_and_b32_e32 v31, 0xffff0000, v51
	v_pk_mul_f32 v[20:21], v[20:21], v[30:31] op_sel_hi:[0,1]
	s_mov_b64 s[8:9], 0x18228500
	v_pk_fma_f32 v[20:21], v[22:23], v[26:27], v[20:21] op_sel_hi:[1,0,1]
	v_lshl_add_u64 v[28:29], v[6:7], 0, s[8:9]
	v_cvt_pk_bf16_f32 v22, v20, v21
	global_store_dword v[28:29], v22, off
	s_and_saveexec_b64 s[8:9], s[4:5]
	s_cbranch_execz .LBB0_384
	v_add_co_u32_e32 v22, vcc, 0x18100000, v4
	s_nop 1
	v_addc_co_u32_e32 v23, vcc, 0, v5, vcc
	global_store_dword v[22:23], v24, off offset:168
.LBB0_384:
	s_or_b64 exec, exec, s[8:9]
	v_add_f32_e32 v19, v24, v19
	v_max_f32_e32 v22, v18, v18
	v_max_f32_e32 v22, v19, v22
	v_sub_f32_e32 v18, v18, v22
	v_sub_f32_e32 v19, v19, v22
	v_mul_f32_e32 v18, 0x3fb8aa3b, v18
	v_mul_f32_e32 v19, 0x3fb8aa3b, v19
	v_exp_f32_e32 v18, v18
	v_exp_f32_e32 v24, v19
	v_lshlrev_b32_e32 v28, 16, v50
	v_and_b32_e32 v29, 0xffff0000, v50
	v_pk_mul_f32 v[18:19], v[18:19], v[28:29] op_sel_hi:[0,1]
	s_mov_b64 s[8:9], 0x1822c580
	v_pk_fma_f32 v[18:19], v[20:21], v[24:25], v[18:19] op_sel_hi:[1,0,1]
	v_lshl_add_u64 v[26:27], v[6:7], 0, s[8:9]
	v_cvt_pk_bf16_f32 v20, v18, v19
	global_store_dword v[26:27], v20, off
	s_and_saveexec_b64 s[8:9], s[4:5]
	s_cbranch_execz .LBB0_386
	v_add_co_u32_e32 v20, vcc, 0x18100000, v4
	s_nop 1
	v_addc_co_u32_e32 v21, vcc, 0, v5, vcc
	global_store_dword v[20:21], v22, off offset:184
.LBB0_386:
	s_or_b64 exec, exec, s[8:9]
	v_add_f32_e32 v17, v22, v17
	v_max_f32_e32 v20, v16, v16
	v_max_f32_e32 v20, v17, v20
	v_sub_f32_e32 v16, v16, v20
	v_sub_f32_e32 v17, v17, v20
	v_mul_f32_e32 v16, 0x3fb8aa3b, v16
	v_mul_f32_e32 v17, 0x3fb8aa3b, v17
	v_exp_f32_e32 v16, v16
	v_exp_f32_e32 v22, v17
	v_lshlrev_b32_e32 v26, 16, v49
	v_and_b32_e32 v27, 0xffff0000, v49
	v_pk_mul_f32 v[16:17], v[16:17], v[26:27] op_sel_hi:[0,1]
	s_mov_b64 s[8:9], 0x18230600
	v_pk_fma_f32 v[16:17], v[18:19], v[22:23], v[16:17] op_sel_hi:[1,0,1]
	v_lshl_add_u64 v[24:25], v[6:7], 0, s[8:9]
	v_cvt_pk_bf16_f32 v18, v16, v17
	global_store_dword v[24:25], v18, off
	s_and_saveexec_b64 s[8:9], s[4:5]
	s_cbranch_execz .LBB0_388
	v_add_co_u32_e32 v18, vcc, 0x18100000, v4
	s_nop 1
	v_addc_co_u32_e32 v19, vcc, 0, v5, vcc
	global_store_dword v[18:19], v20, off offset:200
.LBB0_388:
	s_or_b64 exec, exec, s[8:9]
	v_add_f32_e32 v15, v20, v15
	v_max_f32_e32 v18, v14, v14
	v_max_f32_e32 v18, v15, v18
	v_sub_f32_e32 v14, v14, v18
	v_sub_f32_e32 v15, v15, v18
	v_mul_f32_e32 v14, 0x3fb8aa3b, v14
	v_mul_f32_e32 v15, 0x3fb8aa3b, v15
	v_exp_f32_e32 v14, v14
	v_exp_f32_e32 v20, v15
	v_lshlrev_b32_e32 v24, 16, v48
	v_and_b32_e32 v25, 0xffff0000, v48
	v_pk_mul_f32 v[14:15], v[14:15], v[24:25] op_sel_hi:[0,1]
	s_mov_b64 s[8:9], 0x18234680
	v_pk_fma_f32 v[14:15], v[16:17], v[20:21], v[14:15] op_sel_hi:[1,0,1]
	v_lshl_add_u64 v[22:23], v[6:7], 0, s[8:9]
	v_cvt_pk_bf16_f32 v16, v14, v15
	global_store_dword v[22:23], v16, off
	s_and_saveexec_b64 s[8:9], s[4:5]
	s_cbranch_execz .LBB0_390
	v_add_co_u32_e32 v16, vcc, 0x18100000, v4
	s_nop 1
	v_addc_co_u32_e32 v17, vcc, 0, v5, vcc
	global_store_dword v[16:17], v18, off offset:216
.LBB0_390:
	s_or_b64 exec, exec, s[8:9]
	v_add_f32_e32 v11, v18, v11
	v_max_f32_e32 v16, v10, v10
	v_max_f32_e32 v16, v11, v16
	v_sub_f32_e32 v10, v10, v16
	v_sub_f32_e32 v11, v11, v16
	v_mul_f32_e32 v10, 0x3fb8aa3b, v10
	v_mul_f32_e32 v11, 0x3fb8aa3b, v11
	v_exp_f32_e32 v10, v10
	v_exp_f32_e32 v18, v11
	v_lshlrev_b32_e32 v22, 16, v47
	v_and_b32_e32 v23, 0xffff0000, v47
	v_pk_mul_f32 v[10:11], v[10:11], v[22:23] op_sel_hi:[0,1]
	s_mov_b64 s[8:9], 0x18238700
	v_pk_fma_f32 v[10:11], v[14:15], v[18:19], v[10:11] op_sel_hi:[1,0,1]
	v_lshl_add_u64 v[20:21], v[6:7], 0, s[8:9]
	v_cvt_pk_bf16_f32 v14, v10, v11
	global_store_dword v[20:21], v14, off
	s_and_saveexec_b64 s[8:9], s[4:5]
	s_cbranch_execz .LBB0_392
	v_add_co_u32_e32 v14, vcc, 0x18100000, v4
	s_nop 1
	v_addc_co_u32_e32 v15, vcc, 0, v5, vcc
	global_store_dword v[14:15], v16, off offset:232
.LBB0_392:
	s_or_b64 exec, exec, s[8:9]
	s_mov_b64 s[8:9], 0x1823c780
	v_lshl_add_u64 v[14:15], v[6:7], 0, s[8:9]
	v_add_f32_e32 v6, v16, v9
	v_max_f32_e32 v7, v8, v8
	v_max_f32_e32 v9, v6, v7
	v_sub_f32_e32 v6, v6, v9
	v_mul_f32_e32 v7, 0x3fb8aa3b, v6
	v_sub_f32_e32 v6, v8, v9
	v_mul_f32_e32 v6, 0x3fb8aa3b, v6
	v_exp_f32_e32 v6, v6
	v_exp_f32_e32 v8, v7
	v_lshlrev_b32_e32 v16, 16, v45
	v_and_b32_e32 v17, 0xffff0000, v45
	v_pk_mul_f32 v[6:7], v[6:7], v[16:17] op_sel_hi:[0,1]
	v_pk_fma_f32 v[6:7], v[10:11], v[8:9], v[6:7] op_sel_hi:[1,0,1]
	s_nop 0
	v_cvt_pk_bf16_f32 v8, v6, v7
	global_store_dword v[14:15], v8, off
	s_and_saveexec_b64 s[8:9], s[4:5]
	s_cbranch_execz .LBB0_361
	v_add_co_u32_e32 v4, vcc, 0x18100000, v4
	s_nop 1
	v_addc_co_u32_e32 v5, vcc, 0, v5, vcc
	global_store_dword v[4:5], v9, off offset:248
	s_branch .LBB0_361
